# phase 3: odd workgroups run their chunk-gate unit before their attention units (independent work), overlapping memory-bound and compute-bound halves of the chip
# speedup vs baseline: 1.0153x; 1.0043x over previous
.LBB0_429:
	s_or_b64 exec, exec, s[2:3]
	s_cmpk_lt_i32 s97, 0x400
	s_cselect_b64 s[10:11], -1, 0
	s_cmpk_gt_i32 s97, 0x3ff
	s_waitcnt lgkmcnt(0)
	s_barrier
	s_mov_b32 s98, 0
	s_cbranch_scc1 .LBB0_449
	s_and_b32 s98, s97, 1
	s_cmp_eq_u32 s98, 1
	s_cbranch_scc1 .LBB0_449
.Lp3_attn:
	s_add_u32 s12, s90, 0x17e1c000
	s_mov_b32 s36, 0
	s_addc_u32 s13, s91, 0
	s_waitcnt vmcnt(3)
	v_mov_b32_e32 v150, 0x10000
	s_waitcnt vmcnt(1)
	v_mov_b32_e32 v129, 0
	s_mov_b32 s15, 0x42b504f3
	s_mov_b32 s14, 0x3e0293ee
	v_mov_b32_e32 v151, 0xf149f2ca
	s_mov_b64 s[16:17], 0x8000
	s_mov_b64 s[18:19], 0xc000
	v_mov_b32_e32 v152, 0x120000
	s_mov_b32 s37, s36
	s_mov_b32 s38, s36
	s_mov_b32 s39, s36
	s_mov_b32 s40, s36
	s_mov_b32 s41, s36
	s_mov_b32 s42, s36
	s_mov_b32 s43, s36
	s_mov_b32 s44, s36
	s_mov_b32 s45, s36
	s_mov_b32 s46, s36
	s_mov_b32 s47, s36
	s_mov_b32 s48, s36
	s_mov_b32 s49, s36
	s_mov_b32 s50, s36
	s_mov_b32 s51, s36
	s_mov_b32 s28, 0xffff4000
	s_movk_i32 s29, 0x8000
	s_mov_b32 s30, 0xfedf4000
	s_mov_b32 s31, 0xfedf8000
	s_movk_i32 s34, 0xc000
	s_mov_b32 s35, 0xfedfc000
	s_mov_b32 s55, 0xfee00000
	s_mov_b64 s[20:21], 0x10000
	s_movk_i32 s56, 0x2200
	s_movk_i32 s57, 0x110
	s_movk_i32 s58, 0x440
	s_mov_b32 s59, s97
	s_branch .LBB0_432

.LBB0_449:
	v_readlane_b32 s48, v255, 6
	s_cmpk_gt_i32 s97, 0xff
	v_readlane_b32 s49, v255, 7
	s_cbranch_scc1 .LBB0_458
	s_cmp_eq_u32 s98, 2
	s_cbranch_scc1 .LBB0_458
	v_mbcnt_hi_u32_b32 v100, -1, v246
	s_add_u32 s2, s90, 0x19000020
	v_and_b32_e32 v0, 64, v100
	s_addc_u32 s3, s91, 0
	s_lshl_b32 s1, s97, 7
	s_lshl_b32 s7, s48, 7
	v_xor_b32_e32 v101, 1, v100
	v_add_u32_e32 v102, 64, v0
	v_xor_b32_e32 v103, 2, v100
	s_mov_b32 s6, 0x3a800000
	s_mov_b32 s28, 0x800000
	v_mov_b32_e32 v33, 0
	s_movk_i32 s29, 0xffe0
	s_movk_i32 s30, 0x110
	s_mov_b64 s[8:9], 0x6c00800
	s_mov_b64 s[12:13], 0x19000000
	s_mov_b64 s[14:15], 0x12c00000
	s_mov_b64 s[16:17], 0x100
	s_mov_b64 s[18:19], 0x8000
	s_mov_b32 s31, s97

.LBB0_458:
	s_cmp_eq_u32 s98, 1
	s_cbranch_scc0 .Lp3_done
	s_mov_b32 s98, 2
	s_add_u32 s1, s90, 0x17e00000
	s_addc_u32 s54, s91, 0
	s_branch .Lp3_attn
